# phase X compressed-attention pass 2: the V tile's four serialised load pairs (a full wait before each PV MFMA pair) fetched together at the top of the iteration into spare registers
# speedup vs baseline: 1.0063x; 1.0025x over previous
; #define MFMA32(a, b, c) __builtin_amdgcn_mfma_f32_32x32x16_bf16((a), (b), (c), 0, 0, 0)
; DI float ex2(float x) { return __builtin_amdgcn_exp2f(x); }
; DI int crow(int i, int h) { return (i & 3) + 8 * (i >> 2) + 4 * h; }
; DI f32x16 qk_tile(const bf16x8 (&qf)[4], const bf16_t* krow) {
;   f32x16 s;
; #pragma unroll
;   for (int i = 0; i < 16; ++i) s[i] = 0.f;
; #pragma unroll
;   for (int ss = 0; ss < 4; ++ss) { const bf16x8 kf = *(const bf16x8*)(krow + 512 * ss); s = MFMA32(kf, qf[ss], s); }
;   return s;
; }
; DI void nsa_cmp_item(const Params& p, int item, const unsigned char* blut, const float* tbl, float* impw) {
;     ...
;     for (int kt = 0; kt < ntile; ++kt) {
;       {
;         const f32x16 s = qk_tile(qf, KC + (size_t)kt * 2048 + (h * 32 + r) * 8);
;         float pr[16];
;         int dist[16]; float bv[16];
; #pragma unroll
;         for (int i = 0; i < 16; ++i) dist[i] = t - (16 * (kt * 32 + crow(i, h)) + 31);
;         bias16(blut, tblh, dist, bv);
; #pragma unroll
;         for (int i = 0; i < 16; ++i) pr[i] = (dist[i] >= 0) ? ex2(s[i] + bv[i] - muse) * inv : 0.f;
.LBB0_165:
	v_lshl_add_u64 v[136:137], v[84:85], 0, v[70:71]
	v_add_co_u32_e32 v136, vcc, 0x16c84000, v136
	s_nop 1
	v_addc_co_u32_e32 v137, vcc, 0, v137, vcc
	global_load_dwordx2 v[140:141], v[136:137], off
	global_load_dwordx2 v[142:143], v[136:137], off offset:512
	global_load_dwordx2 v[144:145], v[136:137], off offset:1024
	global_load_dwordx2 v[146:147], v[136:137], off offset:1536
	global_load_dwordx2 v[148:149], v[136:137], off offset:2048
	global_load_dwordx2 v[150:151], v[136:137], off offset:2560
	global_load_dwordx2 v[152:153], v[136:137], off offset:3072
	global_load_dwordx2 v[154:155], v[136:137], off offset:3584
	v_lshl_add_u64 v[32:33], v[84:85], 0, v[78:79]
	s_mov_b32 s26, 0x16c04000
	v_add_co_u32_e32 v36, vcc, s26, v32
	v_add_u32_e32 v100, 0x1b0, v97
	s_nop 0
	v_addc_co_u32_e32 v37, vcc, 0, v33, vcc
	global_load_dwordx4 v[32:35], v[36:37], off
	global_load_dwordx4 v[104:107], v[36:37], off offset:1024
	global_load_dwordx4 v[108:111], v[36:37], off offset:2048
	global_load_dwordx4 v[112:115], v[36:37], off offset:3072
	v_add_u32_e32 v101, 0x1a0, v97
	v_add_u32_e32 v102, 0x190, v97
	v_add_u32_e32 v116, 0x180, v97
	v_add_u32_e32 v117, 0x130, v97
	v_add_u32_e32 v118, 0x120, v97
	v_add_u32_e32 v119, 0x110, v97
	v_add_u32_e32 v120, 0x100, v97
	v_add_u32_e32 v121, 0xb0, v97
	v_add_u32_e32 v122, 0xa0, v97
	v_add_u32_e32 v123, 0x90, v97
	v_add_u32_e32 v124, 0x80, v97
	v_add_u32_e32 v125, 48, v97
	v_add_u32_e32 v126, 32, v97
	v_add_u32_e32 v127, 16, v97
	v_med3_i32 v130, v125, 0, v198
	v_med3_i32 v132, v126, 0, v198
	v_med3_i32 v133, v127, 0, v198
	v_med3_i32 v134, v97, 0, v198
	v_add_u32_e32 v130, 0, v130
	v_add_u32_e32 v132, 0, v132
	v_add_u32_e32 v133, 0, v133
	v_add_u32_e32 v134, 0, v134
	v_cmp_lt_i32_e32 vcc, -1, v100
	s_mov_b32 s26, 0x16c84000
	v_add_u32_e32 v99, -1, v99
	s_waitcnt vmcnt(3)
	v_mfma_f32_32x32x16_bf16 v[32:47], v[32:35], v[48:51], 0
	ds_read_u8 v130, v130
	ds_read_u8 v132, v132
	ds_read_u8 v133, v133
	ds_read_u8 v134, v134
	s_waitcnt vmcnt(2)
	v_mfma_f32_32x32x16_bf16 v[32:47], v[104:107], v[52:55], v[32:47]
	v_med3_i32 v104, v100, 0, v198
	v_med3_i32 v105, v101, 0, v198
	v_med3_i32 v106, v102, 0, v198
	v_med3_i32 v107, v116, 0, v198
	v_add_u32_e32 v104, 0, v104
	v_add_u32_e32 v105, 0, v105
	v_add_u32_e32 v106, 0, v106
	s_waitcnt vmcnt(1)
	v_mfma_f32_32x32x16_bf16 v[32:47], v[108:111], v[56:59], v[32:47]
	v_med3_i32 v108, v117, 0, v198
	v_med3_i32 v109, v118, 0, v198
	v_med3_i32 v110, v119, 0, v198
	v_med3_i32 v111, v120, 0, v198
	v_add_u32_e32 v107, 0, v107
	v_add_u32_e32 v108, 0, v108
	v_add_u32_e32 v109, 0, v109
	s_waitcnt vmcnt(0)
	v_mfma_f32_32x32x16_bf16 v[32:47], v[112:115], v[60:63], v[32:47]
	v_med3_i32 v112, v121, 0, v198
	v_med3_i32 v113, v122, 0, v198
	v_med3_i32 v114, v123, 0, v198
	v_med3_i32 v115, v124, 0, v198
	v_add_u32_e32 v110, 0, v110
	v_add_u32_e32 v111, 0, v111
	v_add_u32_e32 v112, 0, v112
	v_add_u32_e32 v113, 0, v113
	v_add_u32_e32 v114, 0, v114
	v_add_u32_e32 v115, 0, v115
	ds_read_u8 v104, v104
	ds_read_u8 v105, v105
	ds_read_u8 v106, v106
	ds_read_u8 v107, v107
	ds_read_u8 v108, v108
	ds_read_u8 v109, v109
	ds_read_u8 v110, v110
	ds_read_u8 v111, v111
	ds_read_u8 v112, v112
	ds_read_u8 v113, v113
	ds_read_u8 v114, v114
	ds_read_u8 v115, v115
	s_waitcnt lgkmcnt(11)
	s_waitcnt lgkmcnt(10)
	s_waitcnt lgkmcnt(9)
	s_waitcnt lgkmcnt(8)
	s_waitcnt lgkmcnt(7)
	s_waitcnt lgkmcnt(6)
	s_waitcnt lgkmcnt(5)
	s_waitcnt lgkmcnt(4)
	s_waitcnt lgkmcnt(3)
	s_waitcnt lgkmcnt(2)
	s_waitcnt lgkmcnt(1)
	s_waitcnt lgkmcnt(0)
	v_lshl_add_u32 v104, v104, 2, v94
	v_lshl_add_u32 v105, v105, 2, v94
	v_lshl_add_u32 v106, v106, 2, v94
	v_lshl_add_u32 v107, v107, 2, v94
	v_lshl_add_u32 v108, v108, 2, v94
	v_lshl_add_u32 v109, v109, 2, v94
	v_lshl_add_u32 v110, v110, 2, v94
	v_lshl_add_u32 v111, v111, 2, v94
	v_lshl_add_u32 v112, v112, 2, v94
	v_lshl_add_u32 v113, v113, 2, v94
	v_lshl_add_u32 v114, v114, 2, v94
	v_lshl_add_u32 v115, v115, 2, v94
	v_lshl_add_u32 v130, v130, 2, v94
	v_lshl_add_u32 v132, v132, 2, v94
	v_lshl_add_u32 v133, v133, 2, v94
	v_lshl_add_u32 v134, v134, 2, v94
	ds_read_b32 v104, v104 offset:4096
	ds_read_b32 v105, v105 offset:4096
	ds_read_b32 v106, v106 offset:4096
	ds_read_b32 v107, v107 offset:4096
	ds_read_b32 v108, v108 offset:4096
	ds_read_b32 v109, v109 offset:4096
	ds_read_b32 v110, v110 offset:4096
	ds_read_b32 v111, v111 offset:4096
	ds_read_b32 v112, v112 offset:4096
	ds_read_b32 v113, v113 offset:4096
	ds_read_b32 v114, v114 offset:4096
	ds_read_b32 v115, v115 offset:4096
	ds_read_b32 v130, v130 offset:4096
	ds_read_b32 v132, v132 offset:4096
	ds_read_b32 v133, v133 offset:4096
	ds_read_b32 v134, v134 offset:4096
	s_waitcnt lgkmcnt(14)
	s_waitcnt lgkmcnt(13)
	s_waitcnt lgkmcnt(12)
	s_waitcnt lgkmcnt(11)
	s_waitcnt lgkmcnt(10)
	v_add_f32_e32 v32, v32, v104
	v_sub_f32_e32 v32, v32, v95
	v_exp_f32_e32 v32, v32
	s_waitcnt lgkmcnt(9)
	s_waitcnt lgkmcnt(8)
	s_waitcnt lgkmcnt(7)
	s_waitcnt lgkmcnt(6)
	s_waitcnt lgkmcnt(5)
	v_mul_f32_e32 v32, v96, v32
	v_cndmask_b32_e32 v100, 0, v32, vcc
	v_add_f32_e32 v32, v33, v105
	v_sub_f32_e32 v32, v32, v95
	v_exp_f32_e32 v32, v32
	v_cmp_lt_i32_e32 vcc, -1, v101
	s_waitcnt lgkmcnt(4)
	s_waitcnt lgkmcnt(3)
	v_mul_f32_e32 v32, v96, v32
	s_waitcnt lgkmcnt(2)
	s_waitcnt lgkmcnt(1)
	v_cndmask_b32_e32 v33, 0, v32, vcc
	v_add_f32_e32 v32, v34, v106
	v_sub_f32_e32 v32, v32, v95
	v_exp_f32_e32 v32, v32
	v_cmp_lt_i32_e32 vcc, -1, v102
	s_waitcnt lgkmcnt(0)
; #define MFMA32(a, b, c) __builtin_amdgcn_mfma_f32_32x32x16_bf16((a), (b), (c), 0, 0, 0)
; DI float shx32(float v) { const auto r = __builtin_amdgcn_permlane32_swap(__float_as_uint(v), __float_as_uint(v), false, false); return __uint_as_float((threadIdx.x & 32) ? r[0] : r[1]); }
; DI float ex2(float x) { return __builtin_amdgcn_exp2f(x); }
; DI unsigned pack2(float a, float b) { unsigned r; asm("v_cvt_pk_bf16_f32 %0, %1, %2" : "=v"(r) : "v"(a), "v"(b)); return r; }
; DI void pv_tile(AttnSt& st, const float (&pr)[16], const bf16_t* v0, size_t rowstride) {
; #pragma unroll
;   for (int s2 = 0; s2 < 2; ++s2) {
;     u32x4 pk; pk.x = pack2(pr[8 * s2], pr[8 * s2 + 1]); pk.y = pack2(pr[8 * s2 + 2], pr[8 * s2 + 3]); pk.z = pack2(pr[8 * s2 + 4], pr[8 * s2 + 5]); pk.w = pack2(pr[8 * s2 + 6], pr[8 * s2 + 7]);
;     const bf16x8 pb = __builtin_bit_cast(bf16x8, pk);
;     {
;       const s16x4 lo = *(const s16x4*)(v0 + 256 * (s2 * 4 + 0)), hi = *(const s16x4*)(v0 + 256 * (s2 * 4 + 1));
;       const bf16x8 va = __builtin_shufflevector(lo, hi, 0, 1, 2, 3, 4, 5, 6, 7);
;       st.o0 = MFMA32(va, pb, st.o0);
;     }
;     {
;       const s16x4 lo = *(const s16x4*)(v0 + 256 * (s2 * 4 + 2)), hi = *(const s16x4*)(v0 + 256 * (s2 * 4 + 3));
;       const bf16x8 va = __builtin_shufflevector(lo, hi, 0, 1, 2, 3, 4, 5, 6, 7);
;       st.o1 = MFMA32(va, pb, st.o1);
;     }
;   }
; DI void nsa_cmp_item(const Params& p, int item, const unsigned char* blut, const float* tbl, float* impw) {
;     ...
;         for (int i = 0; i < 16; ++i) pr[i] = (dist[i] >= 0) ? ex2(s[i] + bv[i] - muse) * inv : 0.f;
;         float recv[4];
; #pragma unroll
;         for (int q = 0; q < 4; ++q) recv[q] = shx32(pr[4 * q + 3]);
; #pragma unroll
;         for (int q = 0; q < 4; ++q) {
;           const float qs = (pr[4 * q] + pr[4 * q + 1]) + (pr[4 * q + 2] + pr[4 * q + 3]);
;           const float cin = h ? recv[q] : (q ? recv[q > 0 ? q - 1 : 0] : prev3);
;           impw[r * 65 + 8 * kt + 2 * q + h] += qs + cin;
;         }
;         prev3 = recv[3];
;         pv_tile(st, pr, VCT + (size_t)kt * 2048 + (h * 32 + r) * 4, 256);
	v_mul_f32_e32 v32, v96, v32
	v_cndmask_b32_e32 v34, 0, v32, vcc
	v_add_f32_e32 v32, v35, v107
	v_sub_f32_e32 v32, v32, v95
	v_exp_f32_e32 v32, v32
	v_cmp_lt_i32_e32 vcc, -1, v116
	v_mul_f32_e32 v32, v96, v32
	s_nop 0
	v_cndmask_b32_e32 v35, 0, v32, vcc
	v_add_f32_e32 v32, v36, v108
	v_sub_f32_e32 v32, v32, v95
	v_exp_f32_e32 v32, v32
	v_cmp_lt_i32_e32 vcc, -1, v117
	v_mul_f32_e32 v32, v96, v32
	s_nop 0
	v_cndmask_b32_e32 v36, 0, v32, vcc
	v_add_f32_e32 v32, v37, v109
	v_sub_f32_e32 v32, v32, v95
	v_exp_f32_e32 v32, v32
	v_cmp_lt_i32_e32 vcc, -1, v118
	v_mul_f32_e32 v32, v96, v32
	s_nop 0
	v_cndmask_b32_e32 v37, 0, v32, vcc
	v_add_f32_e32 v32, v38, v110
	v_sub_f32_e32 v32, v32, v95
	v_exp_f32_e32 v32, v32
	v_cmp_lt_i32_e32 vcc, -1, v119
	v_mul_f32_e32 v32, v96, v32
	s_nop 0
	v_cndmask_b32_e32 v101, 0, v32, vcc
	v_add_f32_e32 v32, v39, v111
	v_sub_f32_e32 v32, v32, v95
	v_exp_f32_e32 v32, v32
	v_cmp_lt_i32_e32 vcc, -1, v120
	v_mul_f32_e32 v32, v96, v32
	s_nop 0
	v_cndmask_b32_e32 v102, 0, v32, vcc
	v_add_f32_e32 v32, v40, v112
	v_sub_f32_e32 v32, v32, v95
	v_exp_f32_e32 v32, v32
	v_cmp_lt_i32_e32 vcc, -1, v121
	v_add_f32_e32 v109, v101, v102
	v_mul_f32_e32 v32, v96, v32
	v_cndmask_b32_e32 v38, 0, v32, vcc
	v_add_f32_e32 v32, v41, v113
	v_sub_f32_e32 v32, v32, v95
	v_exp_f32_e32 v32, v32
	v_cmp_lt_i32_e32 vcc, -1, v122
	v_mul_f32_e32 v32, v96, v32
	s_nop 0
	v_cndmask_b32_e32 v39, 0, v32, vcc
	v_add_f32_e32 v32, v42, v114
	v_sub_f32_e32 v32, v32, v95
	v_exp_f32_e32 v32, v32
	v_cmp_lt_i32_e32 vcc, -1, v123
	v_mul_f32_e32 v32, v96, v32
	s_nop 0
	v_cndmask_b32_e32 v40, 0, v32, vcc
	v_add_f32_e32 v32, v43, v115
	v_sub_f32_e32 v32, v32, v95
	v_exp_f32_e32 v32, v32
	v_cmp_lt_i32_e32 vcc, -1, v124
	v_mul_f32_e32 v32, v96, v32
	s_nop 0
	v_cndmask_b32_e32 v41, 0, v32, vcc
	v_add_f32_e32 v32, v44, v130
	v_sub_f32_e32 v32, v32, v95
	v_exp_f32_e32 v32, v32
	v_cmp_lt_i32_e32 vcc, -1, v125
	v_mul_f32_e32 v32, v96, v32
	s_nop 0
	v_cndmask_b32_e32 v42, 0, v32, vcc
	v_add_f32_e32 v32, v45, v132
	v_sub_f32_e32 v32, v32, v95
	v_exp_f32_e32 v32, v32
	v_cmp_lt_i32_e32 vcc, -1, v126
	v_mul_f32_e32 v32, v96, v32
	s_nop 0
	v_cndmask_b32_e32 v43, 0, v32, vcc
	v_add_f32_e32 v32, v46, v133
	v_sub_f32_e32 v32, v32, v95
	v_exp_f32_e32 v32, v32
	v_cmp_lt_i32_e32 vcc, -1, v127
	v_mov_b32_e32 v46, v35
	v_mul_f32_e32 v32, v96, v32
	v_cndmask_b32_e32 v44, 0, v32, vcc
	v_add_f32_e32 v32, v47, v134
	v_sub_f32_e32 v32, v32, v95
	v_exp_f32_e32 v32, v32
	v_cmp_lt_i32_e32 vcc, -1, v97
	v_add_f32_e32 v47, v34, v35
	v_add_u32_e32 v97, 0xfffffe00, v97
	v_mul_f32_e32 v32, v96, v32
	v_cndmask_b32_e32 v45, 0, v32, vcc
	v_mov_b32_e32 v32, v35
	s_nop 1
	v_permlane32_swap_b32_e32 v32, v46
	v_cndmask_b32_e64 v106, v32, v46, s[12:13]
	v_mov_b32_e32 v32, v102
	v_mov_b32_e32 v46, v102
	s_nop 1
	v_permlane32_swap_b32_e32 v32, v46
	v_cndmask_b32_e64 v107, v32, v46, s[12:13]
	v_mov_b32_e32 v32, v41
	v_mov_b32_e32 v46, v41
	s_nop 1
	v_permlane32_swap_b32_e32 v32, v46
	v_cndmask_b32_e64 v108, v32, v46, s[12:13]
	v_mov_b32_e32 v32, v45
	v_mov_b32_e32 v46, v45
	s_nop 1
	v_permlane32_swap_b32_e32 v32, v46
	v_cndmask_b32_e64 v32, v32, v46, s[12:13]
	v_add_f32_e32 v46, v100, v33
	v_add_f32_e32 v46, v46, v47
	v_cndmask_b32_e64 v47, v106, v103, s[8:9]
	v_add_f32_e32 v103, v46, v47
	ds_read2_b32 v[46:47], v98 offset1:2
	ds_read2_b32 v[104:105], v98 offset0:4 offset1:6
	v_cndmask_b32_e64 v106, v107, v106, s[8:9]
	s_waitcnt lgkmcnt(1)
	v_add_f32_e32 v46, v46, v103
	v_add_f32_e32 v103, v36, v37
	v_add_f32_e32 v103, v103, v109
	v_add_f32_e32 v103, v103, v106
	v_add_f32_e32 v47, v47, v103
	ds_write2_b32 v98, v46, v47 offset1:2
	v_add_f32_e32 v46, v38, v39
	v_add_f32_e32 v47, v40, v41
	v_add_f32_e32 v46, v46, v47
	v_cndmask_b32_e64 v47, v108, v107, s[8:9]
	v_add_f32_e32 v46, v46, v47
	v_add_f32_e32 v47, v42, v43
	v_add_f32_e32 v103, v44, v45
	v_add_f32_e32 v47, v47, v103
	v_cndmask_b32_e64 v103, v32, v108, s[8:9]
	v_add_f32_e32 v47, v47, v103
	s_waitcnt lgkmcnt(1)
	v_add_f32_e32 v46, v46, v104
	v_add_f32_e32 v47, v47, v105
	ds_write2_b32 v98, v46, v47 offset0:4 offset1:6
	v_lshl_add_u64 v[46:47], v[84:85], 0, v[70:71]
	v_add_co_u32_e32 v46, vcc, s26, v46
	v_cvt_pk_bf16_f32 v105, v34, v35
	v_cvt_pk_bf16_f32 v106, v36, v37
	v_cvt_pk_bf16_f32 v104, v100, v33
	v_cvt_pk_bf16_f32 v107, v101, v102
	s_nop 1
	v_addc_co_u32_e32 v47, vcc, 0, v47, vcc
	s_nop 1
	v_mfma_f32_32x32x16_bf16 v[16:31], v[140:143], v[104:107], v[16:31]
	v_cmp_eq_u32_e32 vcc, 0, v99
	v_add_u32_e32 v98, 32, v98
	v_lshl_add_u64 v[84:85], v[84:85], 0, s[80:81]
	s_or_b64 s[14:15], vcc, s[14:15]
	v_mov_b32_e32 v103, v32
	s_nop 1
	v_mfma_f32_32x32x16_bf16 v[0:15], v[144:147], v[104:107], v[0:15]
	v_cvt_pk_bf16_f32 v34, v38, v39
	v_cvt_pk_bf16_f32 v35, v40, v41
	v_cvt_pk_bf16_f32 v36, v42, v43
	v_cvt_pk_bf16_f32 v37, v44, v45
	s_nop 1
	v_mfma_f32_32x32x16_bf16 v[16:31], v[148:151], v[34:37], v[16:31]
	s_nop 1
	v_mfma_f32_32x32x16_bf16 v[0:15], v[152:155], v[34:37], v[0:15]
	s_andn2_b64 exec, exec, s[14:15]
	s_cbranch_execnz .LBB0_165
; DI void nsa_cmp_item(const Params& p, int item, const unsigned char* blut, const float* tbl, float* impw) {
;     ...
;     const float g0 = gates[head * 3 + 0];
; #pragma unroll
;     for (int i = 0; i < 16; ++i) { st.o0[i] *= g0; st.o1[i] *= g0; }
;     store_o((bf16_t*)(p.ws + OFF_OC) + (size_t)(b * 4096 + t) * 384 + head * 64, st.o0, st.o1, h);
;   }
;   const int cur = t >> 6;
;   unsigned long long mask;
;   if (cur < 16) {
;     mask = (2ull << cur) - 1ull;
;   } else {
;     float own[32], oth[32];
; #pragma unroll
;     for (int j = 0; j < 32; ++j) {
;       const int u = 2 * j + h, uo = 2 * j + 1 - h;
;       const float a = impw[r * 65 + u], bb = impw[r * 65 + uo];
;       own[j] = ((u >= 1) && (u <= cur - 2)) ? a : -1.f;
;       oth[j] = ((uo >= 1) && (uo <= cur - 2)) ? bb : -1.f;
;     }
	s_or_b64 exec, exec, s[14:15]
	v_lshl_add_u32 v130, v93, 1, v93
	v_lshl_add_u64 v[32:33], v[130:131], 2, v[68:69]
	global_load_dword v34, v[32:33], off
	s_add_i32 s23, s23, 1
	v_lshlrev_b32_e32 v130, 1, v82
	s_cmp_eq_u32 s23, 3
	v_lshl_add_u64 v[32:33], v[76:77], 0, v[130:131]
	s_waitcnt vmcnt(0)
	s_nop 0
	v_mul_f32_e32 v35, v0, v34
	v_mul_f32_e32 v0, v17, v34
	v_mul_f32_e32 v17, v1, v34
	v_mul_f32_e32 v1, v18, v34
	v_mul_f32_e32 v16, v16, v34
	v_mul_f32_e32 v18, v2, v34
	v_mul_f32_e32 v2, v19, v34
	v_mul_f32_e32 v3, v3, v34
	v_mul_f32_e32 v19, v20, v34
	v_mul_f32_e32 v20, v4, v34
	v_mul_f32_e32 v4, v21, v34
	v_mul_f32_e32 v21, v5, v34
	v_mul_f32_e32 v5, v22, v34
	v_mul_f32_e32 v22, v6, v34
	v_mul_f32_e32 v6, v23, v34
	v_mul_f32_e32 v7, v7, v34
	v_mul_f32_e32 v23, v24, v34
	v_mul_f32_e32 v24, v8, v34
	v_mul_f32_e32 v8, v25, v34
	v_mul_f32_e32 v25, v9, v34
	v_mul_f32_e32 v9, v26, v34
	v_mul_f32_e32 v26, v10, v34
	v_mul_f32_e32 v10, v27, v34
	v_mul_f32_e32 v11, v11, v34
	v_mul_f32_e32 v27, v28, v34
	v_mul_f32_e32 v28, v12, v34
	v_mul_f32_e32 v12, v29, v34
	v_mul_f32_e32 v29, v13, v34
	v_mul_f32_e32 v13, v30, v34
	v_mul_f32_e32 v30, v14, v34
	v_mul_f32_e32 v14, v31, v34
	v_mul_f32_e32 v15, v15, v34
	v_cvt_pk_bf16_f32 v0, v16, v0
	v_cvt_pk_bf16_f32 v1, v1, v2
	v_cvt_pk_bf16_f32 v2, v35, v17
	v_cvt_pk_bf16_f32 v3, v18, v3
	v_cvt_pk_bf16_f32 v4, v19, v4
	v_cvt_pk_bf16_f32 v5, v5, v6
	v_cvt_pk_bf16_f32 v6, v20, v21
	v_cvt_pk_bf16_f32 v7, v22, v7
	v_cvt_pk_bf16_f32 v8, v23, v8
	v_cvt_pk_bf16_f32 v9, v9, v10
	v_cvt_pk_bf16_f32 v10, v24, v25
	v_cvt_pk_bf16_f32 v11, v26, v11
	v_cvt_pk_bf16_f32 v12, v27, v12
	v_cvt_pk_bf16_f32 v13, v13, v14
	v_cvt_pk_bf16_f32 v14, v28, v29
	v_cvt_pk_bf16_f32 v15, v30, v15
	global_store_dwordx2 v[32:33], v[0:1], off
	global_store_dwordx2 v[32:33], v[2:3], off offset:64
	global_store_dwordx2 v[32:33], v[4:5], off offset:16
	global_store_dwordx2 v[32:33], v[6:7], off offset:80
	global_store_dwordx2 v[32:33], v[8:9], off offset:32
	global_store_dwordx2 v[32:33], v[10:11], off offset:96
	global_store_dwordx2 v[32:33], v[12:13], off offset:48
	global_store_dwordx2 v[32:33], v[14:15], off offset:112
	s_cbranch_scc0 .LBB0_162
	s_movk_i32 s14, 0x3ff
	v_lshrrev_b32_e32 v2, 6, v88
	v_cmp_lt_u32_e32 vcc, s14, v88
	s_and_saveexec_b64 s[14:15], vcc
	s_xor_b64 s[14:15], exec, s[14:15]
	s_cbranch_execz .LBB0_174
	v_xor_b32_e32 v1, 1, v65
	v_lshlrev_b32_e32 v0, 2, v1
	v_add3_u32 v26, v86, v0, v87
	ds_read_b32 v3, v26 offset:8192
	v_mov_b32_e32 v51, -1.0
	s_and_saveexec_b64 s[56:57], s[10:11]
	ds_read_b32 v51, v83 offset:8192
	s_or_b64 exec, exec, s[56:57]
	v_add_u32_e32 v0, -2, v2
	v_sub_co_u32_e32 v16, vcc, 0, v65
	v_cmp_gt_i32_e64 s[10:11], v1, v0
	s_or_b64 s[10:11], vcc, s[10:11]
	v_add_u32_e32 v24, 0x2000, v83
	s_waitcnt lgkmcnt(0)
	v_cndmask_b32_e64 v69, v3, -1.0, s[10:11]
	v_add_u32_e32 v3, 0x2000, v26
	ds_read2_b32 v[4:5], v24 offset0:2 offset1:4
	ds_read2_b32 v[6:7], v24 offset0:6 offset1:8
	ds_read2_b32 v[8:9], v24 offset0:10 offset1:12
	ds_read2_b32 v[10:11], v24 offset0:14 offset1:16
	ds_read2_b32 v[12:13], v3 offset0:2 offset1:6
	ds_read2_b32 v[14:15], v3 offset0:14 offset1:30
	v_lshlrev_b32_e32 v3, 2, v16
	v_add3_u32 v3, v86, v3, v87
	v_add_u32_e32 v44, 0x2000, v3
	v_or_b32_e32 v56, 2, v65
	ds_read2_b32 v[16:17], v44 offset0:5 offset1:9
	v_xor_b32_e32 v1, 3, v65
	v_cmp_le_i32_e32 vcc, v56, v0
	v_or_b32_e32 v59, 4, v65
	v_or_b32_e32 v62, 6, v65
	s_waitcnt lgkmcnt(6)
	v_cndmask_b32_e32 v63, -1.0, v4, vcc
	v_cmp_le_i32_e32 vcc, v1, v0
	v_xor_b32_e32 v1, 5, v65
	v_or_b32_e32 v60, 8, v65
	s_waitcnt lgkmcnt(2)
	v_cndmask_b32_e32 v71, -1.0, v12, vcc
	v_cmp_le_i32_e32 vcc, v59, v0
	v_or_b32_e32 v57, 10, v65
	v_or_b32_e32 v54, 12, v65
	v_cndmask_b32_e32 v70, -1.0, v5, vcc
	v_cmp_le_i32_e32 vcc, v1, v0
	v_xor_b32_e32 v1, 7, v65
	ds_read2_b32 v[4:5], v44 offset0:11 offset1:13
	ds_read2_b32 v[18:19], v44 offset0:17 offset1:19
	s_waitcnt lgkmcnt(2)
	v_cndmask_b32_e32 v72, -1.0, v16, vcc
	v_cmp_le_i32_e32 vcc, v62, v0
	v_or_b32_e32 v52, 14, v65
	v_or_b32_e32 v47, 16, v65
	v_cndmask_b32_e32 v68, -1.0, v6, vcc
	v_cmp_le_i32_e32 vcc, v1, v0
	v_xor_b32_e32 v1, 9, v65
	v_or_b32_e32 v48, 18, v65
	v_cndmask_b32_e32 v73, -1.0, v13, vcc
	v_cmp_le_i32_e32 vcc, v60, v0
	v_or_b32_e32 v42, 20, v65
	v_or_b32_e32 v43, 22, v65
	v_cndmask_b32_e32 v61, -1.0, v7, vcc
	v_cmp_le_i32_e32 vcc, v1, v0
	v_xor_b32_e32 v1, 11, v65
	ds_read2_b32 v[6:7], v44 offset0:21 offset1:23
	v_cndmask_b32_e32 v74, -1.0, v17, vcc
	v_cmp_le_i32_e32 vcc, v57, v0
	v_or_b32_e32 v38, 24, v65
	v_or_b32_e32 v39, 26, v65
	v_cndmask_b32_e32 v58, -1.0, v8, vcc
	v_cmp_le_i32_e32 vcc, v1, v0
	v_xor_b32_e32 v1, 13, v65
	v_or_b32_e32 v25, 28, v65
	s_waitcnt lgkmcnt(2)
	v_cndmask_b32_e32 v75, -1.0, v4, vcc
	v_cmp_le_i32_e32 vcc, v54, v0
	v_or_b32_e32 v27, 30, v65
	v_xor_b32_e32 v3, 33, v65
	v_cndmask_b32_e32 v55, -1.0, v9, vcc
	v_cmp_le_i32_e32 vcc, v1, v0
	v_xor_b32_e32 v1, 15, v65
	v_or_b32_e32 v13, 38, v65
	v_cndmask_b32_e32 v76, -1.0, v5, vcc
	v_cmp_le_i32_e32 vcc, v52, v0
	ds_read2_b32 v[4:5], v24 offset0:18 offset1:20
	v_xor_b32_e32 v8, 39, v65
	v_cndmask_b32_e32 v53, -1.0, v10, vcc
	v_cmp_le_i32_e32 vcc, v1, v0
	v_xor_b32_e32 v1, 17, v65
	v_or_b32_e32 v17, 46, v65
	v_cndmask_b32_e32 v77, -1.0, v14, vcc
	v_cmp_le_i32_e32 vcc, v47, v0
	ds_read2_b32 v[20:21], v44 offset0:51 offset1:53
	ds_read2_b32 v[22:23], v44 offset0:55 offset1:57
	v_cndmask_b32_e32 v49, -1.0, v11, vcc
	v_cmp_le_i32_e32 vcc, v1, v0
	v_xor_b32_e32 v1, 19, v65
	v_or_b32_e32 v11, 34, v65
	s_waitcnt lgkmcnt(4)
	v_cndmask_b32_e32 v78, -1.0, v18, vcc
	v_cmp_le_i32_e32 vcc, v48, v0
	v_xor_b32_e32 v18, 47, v65
	v_xor_b32_e32 v34, 55, v65
	s_waitcnt lgkmcnt(2)
; DI void nsa_cmp_item(const Params& p, int item, const unsigned char* blut, const float* tbl, float* impw) {
;     ...
;     float own[32], oth[32];
; #pragma unroll
;     for (int j = 0; j < 32; ++j) {
;       const int u = 2 * j + h, uo = 2 * j + 1 - h;
;       const float a = impw[r * 65 + u], bb = impw[r * 65 + uo];
;       own[j] = ((u >= 1) && (u <= cur - 2)) ? a : -1.f;
;       oth[j] = ((uo >= 1) && (uo <= cur - 2)) ? bb : -1.f;
;     }
;     float prev = __builtin_inff();
; #pragma unroll 1
;     for (int round = 0; round < 13; ++round) {
;       float m = -2.f;
; #pragma unroll
;       for (int j = 0; j < 32; ++j) { m = fmaxf(m, own[j] < prev ? own[j] : -2.f); m = fmaxf(m, oth[j] < prev ? oth[j] : -2.f); }
;       prev = m;
;     }
	v_cndmask_b32_e32 v50, -1.0, v4, vcc
	v_cmp_le_i32_e32 vcc, v1, v0
	v_xor_b32_e32 v1, 21, v65
	ds_read2_b32 v[100:101], v44 offset0:59 offset1:61
	v_cndmask_b32_e32 v79, -1.0, v19, vcc
	v_cmp_le_i32_e32 vcc, v42, v0
	v_or_b32_e32 v19, 50, v65
	s_mov_b32 s10, 13
	v_cndmask_b32_e32 v45, -1.0, v5, vcc
	ds_read2_b32 v[4:5], v24 offset0:22 offset1:24
	v_cmp_le_i32_e32 vcc, v1, v0
	v_xor_b32_e32 v1, 23, v65
	s_nop 0
	v_cndmask_b32_e32 v80, -1.0, v6, vcc
	v_cmp_le_i32_e32 vcc, v43, v0
	s_waitcnt lgkmcnt(0)
	s_nop 0
	v_cndmask_b32_e32 v46, -1.0, v4, vcc
	v_cmp_le_i32_e32 vcc, v1, v0
	v_xor_b32_e32 v1, 25, v65
	s_nop 0
	v_cndmask_b32_e32 v81, -1.0, v7, vcc
	ds_read2_b32 v[6:7], v44 offset0:25 offset1:27
	v_cmp_le_i32_e32 vcc, v38, v0
	s_nop 1
	v_cndmask_b32_e32 v40, -1.0, v5, vcc
	ds_read2_b32 v[4:5], v24 offset0:26 offset1:28
	v_cmp_le_i32_e32 vcc, v1, v0
	v_xor_b32_e32 v1, 27, v65
	s_waitcnt lgkmcnt(1)
	v_cndmask_b32_e32 v82, -1.0, v6, vcc
	v_cmp_le_i32_e32 vcc, v39, v0
	s_waitcnt lgkmcnt(0)
	s_nop 0
	v_cndmask_b32_e32 v41, -1.0, v4, vcc
	v_cmp_le_i32_e32 vcc, v1, v0
	v_xor_b32_e32 v1, 29, v65
	s_nop 0
	v_cndmask_b32_e32 v84, -1.0, v7, vcc
	ds_read2_b32 v[6:7], v44 offset0:29 offset1:33
	v_cmp_le_i32_e32 vcc, v25, v0
	s_nop 1
	v_cndmask_b32_e32 v36, -1.0, v5, vcc
	ds_read2_b32 v[4:5], v24 offset0:30 offset1:32
	v_cmp_le_i32_e32 vcc, v1, v0
	v_xor_b32_e32 v1, 31, v65
	s_waitcnt lgkmcnt(1)
	v_cndmask_b32_e32 v85, -1.0, v6, vcc
	v_cmp_le_i32_e32 vcc, v27, v0
	s_waitcnt lgkmcnt(0)
	s_nop 0
	v_cndmask_b32_e32 v37, -1.0, v4, vcc
	v_cmp_le_i32_e32 vcc, v1, v0
	v_or_b32_e32 v1, 32, v65
	s_nop 0
	v_cndmask_b32_e32 v86, -1.0, v15, vcc
	v_cmp_le_i32_e32 vcc, v1, v0
	v_or_b32_e32 v15, 42, v65
	s_nop 0
	v_cndmask_b32_e32 v10, -1.0, v5, vcc
	v_cmp_le_i32_e32 vcc, v3, v0
	ds_read2_b32 v[4:5], v24 offset0:34 offset1:36
	v_xor_b32_e32 v3, 35, v65
	v_cndmask_b32_e32 v87, -1.0, v7, vcc
	ds_read2_b32 v[6:7], v44 offset0:35 offset1:37
	v_cmp_le_i32_e32 vcc, v11, v0
	s_waitcnt lgkmcnt(1)
	s_nop 0
	v_cndmask_b32_e32 v28, -1.0, v4, vcc
	v_cmp_le_i32_e32 vcc, v3, v0
	v_or_b32_e32 v3, 36, v65
	v_xor_b32_e32 v4, 37, v65
	s_waitcnt lgkmcnt(0)
	v_cndmask_b32_e32 v88, -1.0, v6, vcc
	v_cmp_le_i32_e32 vcc, v3, v0
	s_nop 1
	v_cndmask_b32_e32 v12, -1.0, v5, vcc
	v_cmp_le_i32_e32 vcc, v4, v0
	ds_read2_b32 v[4:5], v24 offset0:38 offset1:40
	s_nop 0
	v_cndmask_b32_e32 v89, -1.0, v7, vcc
	ds_read2_b32 v[6:7], v44 offset0:39 offset1:41
	v_cmp_le_i32_e32 vcc, v13, v0
	s_waitcnt lgkmcnt(1)
	s_nop 0
	v_cndmask_b32_e32 v29, -1.0, v4, vcc
	v_cmp_le_i32_e32 vcc, v8, v0
	v_or_b32_e32 v4, 40, v65
	ds_read2_b32 v[8:9], v44 offset0:43 offset1:45
	s_waitcnt lgkmcnt(1)
	v_cndmask_b32_e32 v90, -1.0, v6, vcc
	v_xor_b32_e32 v6, 41, v65
	v_cmp_le_i32_e32 vcc, v4, v0
	s_nop 1
	v_cndmask_b32_e32 v14, -1.0, v5, vcc
	v_cmp_le_i32_e32 vcc, v6, v0
	v_xor_b32_e32 v5, 43, v65
	s_nop 0
	v_cndmask_b32_e32 v91, -1.0, v7, vcc
	ds_read2_b32 v[6:7], v24 offset0:42 offset1:44
	v_cmp_le_i32_e32 vcc, v15, v0
	s_waitcnt lgkmcnt(0)
	s_nop 0
	v_cndmask_b32_e32 v30, -1.0, v6, vcc
	v_cmp_le_i32_e32 vcc, v5, v0
	v_or_b32_e32 v5, 44, v65
	v_xor_b32_e32 v6, 45, v65
	v_cndmask_b32_e32 v92, -1.0, v8, vcc
	v_cmp_le_i32_e32 vcc, v5, v0
	s_nop 1
	v_cndmask_b32_e32 v16, -1.0, v7, vcc
	v_cmp_le_i32_e32 vcc, v6, v0
	ds_read2_b32 v[6:7], v24 offset0:46 offset1:48
	s_nop 0
	v_cndmask_b32_e32 v93, -1.0, v9, vcc
	ds_read2_b32 v[8:9], v44 offset0:47 offset1:49
	v_cmp_le_i32_e32 vcc, v17, v0
	v_xor_b32_e32 v44, 61, v65
	s_waitcnt lgkmcnt(1)
	v_cndmask_b32_e32 v31, -1.0, v6, vcc
	v_cmp_le_i32_e32 vcc, v18, v0
	v_or_b32_e32 v6, 48, v65
	s_waitcnt lgkmcnt(0)
	v_cndmask_b32_e32 v94, -1.0, v8, vcc
	v_xor_b32_e32 v8, 49, v65
	v_cmp_le_i32_e32 vcc, v6, v0
	s_nop 1
	v_cndmask_b32_e32 v18, -1.0, v7, vcc
	v_cmp_le_i32_e32 vcc, v8, v0
	v_xor_b32_e32 v7, 51, v65
	s_nop 0
	v_cndmask_b32_e32 v95, -1.0, v9, vcc
	ds_read2_b32 v[8:9], v24 offset0:50 offset1:52
	v_cmp_le_i32_e32 vcc, v19, v0
	s_waitcnt lgkmcnt(0)
	s_nop 0
	v_cndmask_b32_e32 v32, -1.0, v8, vcc
	v_cmp_le_i32_e32 vcc, v7, v0
	v_or_b32_e32 v7, 52, v65
	v_xor_b32_e32 v8, 53, v65
	v_cndmask_b32_e32 v96, -1.0, v20, vcc
	v_cmp_le_i32_e32 vcc, v7, v0
	s_nop 1
	v_cndmask_b32_e32 v20, -1.0, v9, vcc
	v_cmp_le_i32_e32 vcc, v8, v0
	ds_read2_b32 v[8:9], v24 offset0:54 offset1:56
	s_nop 0
	v_cndmask_b32_e32 v97, -1.0, v21, vcc
	v_or_b32_e32 v21, 54, v65
	v_cmp_le_i32_e32 vcc, v21, v0
	s_waitcnt lgkmcnt(0)
	s_nop 0
	v_cndmask_b32_e32 v33, -1.0, v8, vcc
	v_cmp_le_i32_e32 vcc, v34, v0
	v_or_b32_e32 v8, 56, v65
	v_xor_b32_e32 v34, 57, v65
	v_cndmask_b32_e32 v98, -1.0, v22, vcc
	v_cmp_le_i32_e32 vcc, v8, v0
	s_nop 1
	v_cndmask_b32_e32 v22, -1.0, v9, vcc
	v_cmp_le_i32_e32 vcc, v34, v0
	ds_read2_b32 v[34:35], v24 offset0:58 offset1:60
	v_xor_b32_e32 v9, 59, v65
	v_cndmask_b32_e32 v99, -1.0, v23, vcc
	v_or_b32_e32 v23, 58, v65
	v_cmp_le_i32_e32 vcc, v23, v0
	s_waitcnt lgkmcnt(0)
	s_nop 0
	v_cndmask_b32_e32 v34, -1.0, v34, vcc
	v_cmp_le_i32_e32 vcc, v9, v0
	v_or_b32_e32 v9, 60, v65
	s_nop 0
	v_cndmask_b32_e32 v100, -1.0, v100, vcc
	v_cmp_le_i32_e32 vcc, v9, v0
	s_nop 1
	v_cndmask_b32_e32 v24, -1.0, v35, vcc
	ds_read_b32 v102, v26 offset:8440
	ds_read_b32 v35, v83 offset:8440
	v_cmp_le_i32_e32 vcc, v44, v0
	v_or_b32_e32 v26, 62, v65
	v_xor_b32_e32 v44, 63, v65
	v_cndmask_b32_e32 v83, -1.0, v101, vcc
	v_cmp_le_i32_e32 vcc, v26, v0
	s_waitcnt lgkmcnt(0)
	s_nop 0
	v_cndmask_b32_e32 v35, -1.0, v35, vcc
	v_cmp_le_i32_e32 vcc, v44, v0
	v_max_f32_e32 v44, v51, v51
	s_nop 0
	v_cndmask_b32_e32 v101, -1.0, v102, vcc
	v_max_f32_e32 v102, -2.0, v44
	v_mov_b32_e32 v44, 0x7f800000
